# v63 + RWKV waves 0-3: next-chunk triangle tile operand reads issued right after the last-interval barrier (own registers), overlapping epilogue-operand loads and state update
# baseline (speedup 1.0000x reference)
; #define LAS __attribute__((address_space(3)))
; __device__ __forceinline__ f32x4 mfma16(bf16x8 a, bf16x8 b, f32x4 c) { return __builtin_amdgcn_mfma_f32_16x16x32_bf16(a, b, c, 0, 0, 0); }
; __device__ __forceinline__ void lds_barrier() { asm volatile("s_waitcnt lgkmcnt(0)" ::: "memory"); __builtin_amdgcn_s_barrier(); asm volatile("" ::: "memory"); }
; __device__ __forceinline__ void rwkv_chunk_item(const P& p, const Ctx& c, int seg, int w, bool save) {
;     ...
;     auto gtile = [&](int pb, int l15, int quad) {
;         LAS bf16_t* EA = (LAS bf16_t*)(OB + pb * OPB + O_EA); LAS bf16_t* EB = (LAS bf16_t*)(OB + pb * OPB + O_EB);
;         LAS bf16_t* MT1 = (LAS bf16_t*)(OB + pb * OPB + O_MT1); LAS bf16_t* NT = (LAS bf16_t*)(OB + pb * OPB + O_NT); LAS float* MABT = (LAS float*)(OB + pb * OPB + O_MABT);
;         const int sb = c.wv >> 1, tb = c.wv & 1; f32x4 g = (f32x4){0.f, 0.f, 0.f, 0.f};
; #pragma unroll
;         for (int kk = 0; kk < 2; ++kk) g = mfma16(*(const LAS bf16x8*)(EB + (sb * 16 + l15) * 72 + kk * 32 + quad * 8), *(const LAS bf16x8*)(EA + (tb * 16 + l15) * 72 + kk * 32 + quad * 8), g);
;     ...
;         lds_barrier();
;         if (c.wv >= 4) {
;             Zt = mfma16(*(const LAS bf16x8*)(UV + (mtq * 16 + l15) * 40 + quad * 8), *(const LAS bf16x8*)(NT + l15 * 40 + quad * 8), Zt);
;             *(LAS f32x4*)(YB + l15 * 68 + mtq * 16 + quad * 4) = Zt;
;         } else eload(ch);
; #pragma unroll
;         for (int x = 0; x < 2; ++x) { const int ti = c.wv * 2 + x, mt = ti >> 2, nt = ti & 3;
;             S[x] = mfma16(*(const LAS bf16x8*)(UV + (mt * 16 + l15) * 40 + quad * 8), *(const LAS bf16x8*)(EBT + (nt * 16 + l15) * 40 + quad * 8), S[x]);
.LBB0_896:
	s_waitcnt lgkmcnt(0)
	s_barrier
	v_lshlrev_b32_e32 v52, 3, v83
	v_add_u32_e32 v136, s45, v82
	v_lshl_add_u32 v134, v52, 1, s88
	v_mov_b32_e32 v135, 0
	v_mad_u64_u32 v[136:137], s[2:3], v136, s64, v[134:135]
	ds_read_b128 v[130:133], v136 offset:14336
	v_add_u32_e32 v138, s34, v82
	v_mad_u64_u32 v[136:137], s[2:3], v138, s64, v[134:135]
	ds_read_b128 v[148:151], v136 offset:9216
	v_add_u32_e32 v136, s66, v82
	v_mad_u64_u32 v[136:137], s[2:3], v136, s64, v[134:135]
	ds_read_b128 v[124:127], v136 offset:9216
	v_lshl_add_u32 v128, v138, 2, s88
	v_add_u32_e32 v128, 0x5800, v128
	ds_read2_b32 v[152:153], v128 offset0:192 offset1:208
	s_and_b64 vcc, exec, s[68:69]
	s_cbranch_vccz .Lrw_mbr_skip
	s_xor_b32 s78, s87, 1
	s_mulk_i32 s78, 0x5c00
	s_add_i32 s78, s78, 0
	v_add_u32_e32 v176, s67, v82
	v_mul_lo_u32 v176, v176, s63
	v_lshlrev_b32_e32 v177, 1, v52
	v_add_u32_e32 v178, s83, v82
	v_add3_u32 v176, s78, v176, v177
	v_mul_lo_u32 v178, v178, s63
	v_add3_u32 v178, s78, v178, v177
	ds_read_b128 v[154:157], v176 offset:4608
	ds_read_b128 v[158:161], v178
	ds_read_b128 v[162:165], v176 offset:4672
	ds_read_b128 v[166:169], v178 offset:64

; #define LAS __attribute__((address_space(3)))
; __device__ __forceinline__ bf16_t f2bf(float f) { const __bf16 r = (__bf16)f; bf16_t u; __builtin_memcpy(&u, &r, 2); return u; }
; __device__ __forceinline__ f32x4 mfma16(bf16x8 a, bf16x8 b, f32x4 c) { return __builtin_amdgcn_mfma_f32_16x16x32_bf16(a, b, c, 0, 0, 0); }
; __device__ __forceinline__ void rwkv_chunk_item(const P& p, const Ctx& c, int seg, int w, bool save) {
;     ...
;     auto gtile = [&](int pb, int l15, int quad) {
;         LAS bf16_t* EA = (LAS bf16_t*)(OB + pb * OPB + O_EA); LAS bf16_t* EB = (LAS bf16_t*)(OB + pb * OPB + O_EB);
;         LAS bf16_t* MT1 = (LAS bf16_t*)(OB + pb * OPB + O_MT1); LAS bf16_t* NT = (LAS bf16_t*)(OB + pb * OPB + O_NT); LAS float* MABT = (LAS float*)(OB + pb * OPB + O_MABT);
;         const int sb = c.wv >> 1, tb = c.wv & 1; f32x4 g = (f32x4){0.f, 0.f, 0.f, 0.f};
; #pragma unroll
;         for (int kk = 0; kk < 2; ++kk) g = mfma16(*(const LAS bf16x8*)(EB + (sb * 16 + l15) * 72 + kk * 32 + quad * 8), *(const LAS bf16x8*)(EA + (tb * 16 + l15) * 72 + kk * 32 + quad * 8), g);
; #pragma unroll
;         for (int jj = 0; jj < 4; ++jj) { const int s2 = quad * 4 + jj, tt = l15; const float v = g[jj];
;             if (tb == 0) { const float m = (s2 < tt) ? v : 0.f; if (sb == 0) { MABT[s2 * 20 + tt] = m; MT1[tt * 40 + s2] = 0; } else MT1[tt * 40 + 16 + s2] = f2bf(m); }
;             else { const float m = (s2 <= tt) ? v : 0.f; NT[tt * 40 + sb * 16 + s2] = f2bf(m); } } };
;     ...
; #pragma unroll
;         for (int x = 0; x < 2; ++x) { const int ti = c.wv * 2 + x, mt = ti >> 2, nt = ti & 3;
;             S[x] = mfma16(*(const LAS bf16x8*)(UV + (mt * 16 + l15) * 40 + quad * 8), *(const LAS bf16x8*)(EBT + (nt * 16 + l15) * 40 + quad * 8), S[x]);
;             const float gt = GT[nt * 16 + l15];
; #pragma unroll
;             for (int jj = 0; jj < 4; ++jj) S[x][jj] *= gt; }
;         simg(l15, quad);
;         if (c.wv < 4 && ch + 1 < SEGT / 16) gtile(pb ^ 1, l15, quad);
.LBB0_900:
	s_waitcnt lgkmcnt(6)
	v_mfma_f32_16x16x32_bf16 v[6:9], v[130:133], v[148:151], v[6:9]
	s_waitcnt lgkmcnt(4)
	v_mfma_f32_16x16x32_bf16 v[10:13], v[130:133], v[124:127], v[10:13]
	v_mov_b32_e32 v2, v153
	v_lshlrev_b32_e32 v38, 2, v83
	s_nop 7
	v_pk_mul_f32 v[6:7], v[152:153], v[6:7] op_sel_hi:[0,1]
	s_nop 4
	v_pk_mul_f32 v[10:11], v[2:3], v[10:11] op_sel_hi:[0,1]
	v_pk_mul_f32 v[12:13], v[2:3], v[12:13] op_sel_hi:[0,1]
	v_add_u32_e32 v2, s45, v38
	v_lshlrev_b32_e32 v22, 1, v82
	v_mul_lo_u32 v2, v2, s63
	v_pk_mul_f32 v[8:9], v[152:153], v[8:9] op_sel_hi:[0,1]
	v_add3_u32 v2, s40, v22, v2
	v_and_b32_e32 v140, 1, v82
	v_cmp_ne_u32_e64 s[2:3], 0, v140
	v_mov_b32_e32 v141, 0x5040100
	v_mov_b32_e32 v142, 0x3020706
	v_mul_u32_u24_e32 v140, 0x11e, v140
	v_cndmask_b32_e64 v141, v141, v142, s[2:3]
	v_add_u32_e32 v140, v2, v140
	v_cvt_pk_bf16_f32 v22, v6, v8
	v_cvt_pk_bf16_f32 v23, v7, v9
	v_cvt_pk_bf16_f32 v142, v10, v12
	v_cvt_pk_bf16_f32 v143, v11, v13
	v_mov_b32_dpp v144, v22 quad_perm:[1,0,3,2] row_mask:0xf bank_mask:0xf bound_ctrl:1
	v_mov_b32_dpp v145, v23 quad_perm:[1,0,3,2] row_mask:0xf bank_mask:0xf bound_ctrl:1
	v_mov_b32_dpp v146, v142 quad_perm:[1,0,3,2] row_mask:0xf bank_mask:0xf bound_ctrl:1
	v_mov_b32_dpp v147, v143 quad_perm:[1,0,3,2] row_mask:0xf bank_mask:0xf bound_ctrl:1
	v_perm_b32 v22, v144, v22, v141
	v_perm_b32 v23, v145, v23, v141
	v_perm_b32 v142, v146, v142, v141
	v_perm_b32 v143, v147, v143, v141
	s_or_b64 s[2:3], s[56:57], s[4:5]
	ds_write_b32 v140, v22 offset:47104
	ds_write_b32 v140, v23 offset:47248
	ds_write_b32 v140, v142 offset:47136
	s_and_b64 vcc, exec, s[2:3]
	ds_write_b32 v140, v143 offset:47280
	s_cbranch_vccnz .LBB0_929
	s_xor_b32 s2, s87, 1
	s_mulk_i32 s2, 0x5c00
	s_add_i32 s4, s2, 0
	s_waitcnt lgkmcnt(4)
	v_mfma_f32_16x16x32_bf16 v[22:25], v[154:157], v[158:161], 0
	v_add_u32_e32 v39, s4, v84
	v_add_u32_e32 v2, s84, v39
	v_mfma_f32_16x16x32_bf16 v[22:25], v[162:165], v[166:169], v[22:25]
	v_lshl_add_u32 v40, v38, 1, v2
	v_lshl_add_u32 v41, v38, 1, v39
	v_lshl_add_u32 v2, v82, 2, s4
	v_or_b32_e32 v42, 1, v38
	v_or_b32_e32 v43, 2, v38
	v_or_b32_e32 v140, 3, v38
	s_and_b64 vcc, exec, s[72:73]
	s_nop 3
	s_cbranch_vccz .Lrw_mb_notA
	v_cmp_le_i32_e32 vcc, v38, v82
	s_nop 1
	v_cndmask_b32_e32 v22, 0, v22, vcc
	v_cmp_le_i32_e32 vcc, v42, v82
	s_nop 1
	v_cndmask_b32_e32 v23, 0, v23, vcc
	v_cmp_le_i32_e32 vcc, v43, v82
	s_nop 1
	v_cndmask_b32_e32 v24, 0, v24, vcc
	v_cmp_le_i32_e32 vcc, v140, v82
	s_nop 1
	v_cndmask_b32_e32 v25, 0, v25, vcc
	v_cvt_pk_bf16_f32 v22, v22, v23
	v_cvt_pk_bf16_f32 v24, v24, v25
	ds_write_b32 v40, v22 offset:20736
	ds_write_b32 v40, v24 offset:20740
	s_branch .LBB0_929
